# in-proj epilogue: nt hint on the row-major q/k (rope) P1 stores, consumed two phases later; on top of v23
# baseline (speedup 1.0000x reference)
; __device__ __forceinline__ unsigned cvt_pk_bf16(float lo, float hi) { unsigned r; asm volatile("v_cvt_pk_bf16_f32 %0, %1, %2" : "=v"(r) : "v"(lo), "v"(hi)); return r; }
;     __device__ __forceinline__ void operator()(const f32x4 (&acc)[2][2][4][2], const Unit& u, int wr, int wc, int fr, int fq) const {
;     ...
;                 for (int m = 0; m < 4; ++m) { const int row = row0 + ai * HALF + m * 16, t = row & 4095, p = t & 127;
;                     c4[m] = *(const f32x4*)(cs + t * 64 + 16 * wc + 4 * fq); s4[m] = *(const f32x4*)(sn + t * 64 + 16 * wc + 4 * fq);
;                     sc[m][0] = dtab[hb * 128 + p]; sc[m][1] = dtab[(hb + 1) * 128 + p]; }
;                 __builtin_amdgcn_sched_barrier(0);
; #pragma unroll
;                 for (int m = 0; m < 4; ++m) { bf16_t* rowp = O + (size_t)(row0 + ai * HALF + m * 16) * 3072 + col0;
; #pragma unroll
;                     for (int bj = 0; bj < 2; ++bj) {
;                         const float s_ = sc[m][bj]; const f32x4 cc = c4[m], ss = s4[m];
;                         const f32x4 v0 = acc[ai][bj][m][0], v1 = acc[ai][bj][m][1];
;                         u32x4 w;
;                         w.x = cvt_pk_bf16((v0[0] * cc[0] - v0[1] * ss[0]) * s_, (v0[0] * ss[0] + v0[1] * cc[0]) * s_);
;                         w.y = cvt_pk_bf16((v0[2] * cc[1] - v0[3] * ss[1]) * s_, (v0[2] * ss[1] + v0[3] * cc[1]) * s_);
;                         w.z = cvt_pk_bf16((v1[0] * cc[2] - v1[1] * ss[2]) * s_, (v1[0] * ss[2] + v1[1] * cc[2]) * s_);
;                         w.w = cvt_pk_bf16((v1[2] * cc[3] - v1[3] * ss[3]) * s_, (v1[2] * ss[3] + v1[3] * cc[3]) * s_);
;                         *(u32x4*)(rowp + bj * HALF) = w;
;                         if (u.pn >= 8) {
;                             const int tokrow = row0 + ai * HALF + m * 16, odd = fr & 1;
;                             bf16_t* kt = KT + (size_t)((hb + bj) * 128 + wc * 32 + 8 * fq + odd) * ldk + (tokrow - odd);
; #pragma unroll
;                             for (int q = 0; q < 4; ++q) { const unsigned mine = w[q], other = (unsigned)__shfl_xor((int)mine, 1);
.LBB0_535:
	s_cmp_gt_i32 s6, 7
	s_cselect_b64 s[80:81], -1, 0
	s_and_b64 s[16:17], s[80:81], exec
	s_mov_b32 s16, 0x581000
	s_cselect_b32 s16, s16, 0x580000
	v_and_b32_e32 v132, 0xfcf, v210
	s_add_u32 s78, s86, s16
	v_lshlrev_b32_e32 v128, 8, v132
	v_mov_b32_e32 v129, v163
	s_addc_u32 s79, s87, 0
	s_and_b32 s71, s7, 0x100
	s_waitcnt lgkmcnt(0)
	v_lshl_add_u64 v[130:131], v[178:179], 0, v[128:129]
	v_lshl_add_u64 v[128:129], v[180:181], 0, v[128:129]
	global_load_dwordx4 v[152:155], v[130:131], off
	global_load_dwordx4 v[156:159], v[128:129], off
	v_or_b32_e32 v128, s71, v208
	v_lshlrev_b32_e32 v186, 2, v128
	v_or_b32_e32 v128, 16, v132
	s_movk_i32 s7, 0x5f
	v_lshlrev_b32_e32 v128, 8, v128
	v_mov_b32_e32 v129, v163
	v_bitop3_b32 v133, v132, s7, 16 bitop3:0xc8
	v_lshl_add_u64 v[130:131], v[178:179], 0, v[128:129]
	v_lshl_add_u64 v[128:129], v[180:181], 0, v[128:129]
	global_load_dwordx4 v[144:147], v[130:131], off
	global_load_dwordx4 v[148:151], v[128:129], off
	v_or_b32_e32 v128, s71, v133
	v_lshlrev_b32_e32 v128, 2, v128
	global_load_dword v215, v128, s[78:79]
	global_load_dword v214, v128, s[78:79] offset:512
	v_or_b32_e32 v128, 32, v132
	s_movk_i32 s7, 0x6f
	v_lshlrev_b32_e32 v128, 8, v128
	v_mov_b32_e32 v129, v163
	v_bitop3_b32 v133, v132, s7, 32 bitop3:0xc8
	v_lshl_add_u64 v[130:131], v[178:179], 0, v[128:129]
	v_lshl_add_u64 v[128:129], v[180:181], 0, v[128:129]
	global_load_dwordx4 v[136:139], v[130:131], off
	global_load_dwordx4 v[140:143], v[128:129], off
	v_or_b32_e32 v128, s71, v133
	v_lshlrev_b32_e32 v128, 2, v128
	s_movk_i32 s7, 0x7f
	global_load_dword v213, v128, s[78:79]
	global_load_dword v212, v128, s[78:79] offset:512
	v_or_b32_e32 v128, 48, v132
	v_bitop3_b32 v187, v132, s7, 48 bitop3:0xc8
	v_lshlrev_b32_e32 v128, 8, v128
	v_mov_b32_e32 v129, v163
	v_or_b32_e32 v187, s71, v187
	v_lshl_add_u64 v[130:131], v[178:179], 0, v[128:129]
	v_lshl_add_u64 v[132:133], v[180:181], 0, v[128:129]
	v_lshlrev_b32_e32 v187, 2, v187
	global_load_dwordx4 v[128:131], v[130:131], off
	s_nop 0
	global_load_dwordx4 v[132:135], v[132:133], off
	s_nop 0
	global_load_dword v217, v186, s[78:79]
	global_load_dword v216, v186, s[78:79] offset:512
	global_load_dword v211, v187, s[78:79]
	s_nop 0
	global_load_dword v187, v187, s[78:79] offset:512
	s_cmp_lt_i32 s6, 8
	s_waitcnt vmcnt(0)
	v_mov_b32_e32 v192, v152
	v_mov_b32_e32 v193, v156
	v_pk_mul_f32 v[194:195], v[124:125], v[192:193]
	v_mov_b32_e32 v198, v158
	v_sub_f32_e32 v194, v194, v195
	v_mul_f32_e32 v196, v217, v194
	v_mov_b32_e32 v194, v156
	v_mov_b32_e32 v195, v152
	v_pk_mul_f32 v[124:125], v[124:125], v[194:195]
	v_mov_b32_e32 v156, v153
	v_add_f32_e32 v124, v125, v124
	v_mul_f32_e32 v124, v217, v124
	v_mov_b32_e32 v152, v157
	v_cvt_pk_bf16_f32 v124, v196, v124
	v_pk_mul_f32 v[196:197], v[126:127], v[156:157]
	v_pk_mul_f32 v[126:127], v[126:127], v[152:153]
	v_sub_f32_e32 v125, v196, v197
	v_add_f32_e32 v126, v127, v126
	v_mul_f32_e32 v125, v217, v125
	v_mul_f32_e32 v126, v217, v126
	v_mov_b32_e32 v196, v154
	v_mov_b32_e32 v197, v158
	v_mov_b32_e32 v199, v154
	v_cvt_pk_bf16_f32 v125, v125, v126
	v_pk_mul_f32 v[126:127], v[120:121], v[196:197]
	v_pk_mul_f32 v[120:121], v[120:121], v[198:199]
	v_sub_f32_e32 v126, v126, v127
	v_add_f32_e32 v120, v121, v120
	v_mul_f32_e32 v126, v217, v126
	v_mul_f32_e32 v120, v217, v120
	v_mov_b32_e32 v158, v155
	v_mov_b64_e32 v[188:189], s[64:65]
	v_cvt_pk_bf16_f32 v126, v126, v120
	v_pk_mul_f32 v[120:121], v[122:123], v[158:159]
	v_mad_i64_i32 v[188:189], s[6:7], v210, s47, v[188:189]
	v_sub_f32_e32 v120, v120, v121
	v_mov_b32_e32 v154, v159
	v_lshl_add_u64 v[190:191], v[162:163], 1, v[188:189]
	v_sub_u32_e32 v188, v210, v176
	v_mul_f32_e32 v127, v217, v120
	v_pk_mul_f32 v[120:121], v[122:123], v[154:155]
	v_ashrrev_i32_e32 v189, 31, v188
	v_add_f32_e32 v120, v121, v120
	v_mul_f32_e32 v120, v217, v120
	v_cvt_pk_bf16_f32 v127, v127, v120
	global_store_dwordx4 v[190:191], v[124:127], off nt
	s_cbranch_scc1 .LBB0_553
	v_cmp_lt_i32_e32 vcc, v228, v222
	s_nop 1
	v_cndmask_b32_e32 v120, v221, v228, vcc
	v_lshlrev_b32_e32 v122, 2, v120
	ds_bpermute_b32 v120, v122, v124
	s_and_saveexec_b64 s[6:7], s[2:3]
	s_xor_b64 s[6:7], exec, s[6:7]
	s_cbranch_execz .LBB0_538
	s_waitcnt lgkmcnt(0)
	v_lshrrev_b32_e32 v120, 16, v120
	v_and_or_b32 v123, v124, s60, v120

; __device__ __forceinline__ unsigned cvt_pk_bf16(float lo, float hi) { unsigned r; asm volatile("v_cvt_pk_bf16_f32 %0, %1, %2" : "=v"(r) : "v"(lo), "v"(hi)); return r; }
;     __device__ __forceinline__ void operator()(const f32x4 (&acc)[2][2][4][2], const Unit& u, int wr, int wc, int fr, int fq) const {
;     ...
;                         const float s_ = sc[m][bj]; const f32x4 cc = c4[m], ss = s4[m];
;                         const f32x4 v0 = acc[ai][bj][m][0], v1 = acc[ai][bj][m][1];
;                         u32x4 w;
;                         w.x = cvt_pk_bf16((v0[0] * cc[0] - v0[1] * ss[0]) * s_, (v0[0] * ss[0] + v0[1] * cc[0]) * s_);
;                         w.y = cvt_pk_bf16((v0[2] * cc[1] - v0[3] * ss[1]) * s_, (v0[2] * ss[1] + v0[3] * cc[1]) * s_);
;                         w.z = cvt_pk_bf16((v1[0] * cc[2] - v1[1] * ss[2]) * s_, (v1[0] * ss[2] + v1[1] * cc[2]) * s_);
;                         w.w = cvt_pk_bf16((v1[2] * cc[3] - v1[3] * ss[3]) * s_, (v1[2] * ss[3] + v1[3] * cc[3]) * s_);
;                         *(u32x4*)(rowp + bj * HALF) = w;
.LBB0_553:
	v_pk_mul_f32 v[120:121], v[116:117], v[192:193]
	v_pk_mul_f32 v[116:117], v[116:117], v[194:195]
	v_sub_f32_e32 v120, v120, v121
	v_add_f32_e32 v116, v117, v116
	v_mul_f32_e32 v120, v216, v120
	v_mul_f32_e32 v116, v216, v116
	v_cvt_pk_bf16_f32 v116, v120, v116
	v_pk_mul_f32 v[120:121], v[118:119], v[156:157]
	v_pk_mul_f32 v[118:119], v[118:119], v[152:153]
	v_sub_f32_e32 v117, v120, v121
	v_add_f32_e32 v118, v119, v118
	v_mul_f32_e32 v117, v216, v117
	v_mul_f32_e32 v118, v216, v118
	v_cvt_pk_bf16_f32 v117, v117, v118
	v_pk_mul_f32 v[118:119], v[112:113], v[196:197]
	v_pk_mul_f32 v[112:113], v[112:113], v[198:199]
	v_sub_f32_e32 v118, v118, v119
	v_add_f32_e32 v112, v113, v112
	v_mul_f32_e32 v118, v216, v118
	v_mul_f32_e32 v112, v216, v112
	v_cvt_pk_bf16_f32 v118, v118, v112
	v_pk_mul_f32 v[112:113], v[114:115], v[158:159]
	s_andn2_b64 vcc, exec, s[80:81]
	v_sub_f32_e32 v112, v112, v113
	v_mul_f32_e32 v119, v216, v112
	v_pk_mul_f32 v[112:113], v[114:115], v[154:155]
	s_nop 0
	v_add_f32_e32 v112, v113, v112
	v_mul_f32_e32 v112, v216, v112
	v_cvt_pk_bf16_f32 v119, v119, v112
	v_cndmask_b32_e64 v112, 0, 1, s[80:81]
	v_cmp_ne_u32_e64 s[6:7], 1, v112
	global_store_dwordx4 v[190:191], v[116:119], off offset:256 nt
	s_cbranch_vccnz .LBB0_571
	v_cmp_lt_i32_e32 vcc, v228, v222
	s_nop 1
	v_cndmask_b32_e32 v112, v221, v228, vcc
	v_lshlrev_b32_e32 v114, 2, v112
	ds_bpermute_b32 v112, v114, v116
	s_and_saveexec_b64 s[16:17], s[2:3]
	s_xor_b64 s[16:17], exec, s[16:17]
	s_cbranch_execz .LBB0_556
	s_waitcnt lgkmcnt(0)
	v_lshrrev_b32_e32 v112, 16, v112
	v_and_or_b32 v115, v116, s60, v112

; __device__ __forceinline__ unsigned cvt_pk_bf16(float lo, float hi) { unsigned r; asm volatile("v_cvt_pk_bf16_f32 %0, %1, %2" : "=v"(r) : "v"(lo), "v"(hi)); return r; }
;     __device__ __forceinline__ void operator()(const f32x4 (&acc)[2][2][4][2], const Unit& u, int wr, int wc, int fr, int fq) const {
;     ...
;                 for (int m = 0; m < 4; ++m) { bf16_t* rowp = O + (size_t)(row0 + ai * HALF + m * 16) * 3072 + col0;
; #pragma unroll
;                     for (int bj = 0; bj < 2; ++bj) {
;                         const float s_ = sc[m][bj]; const f32x4 cc = c4[m], ss = s4[m];
;                         const f32x4 v0 = acc[ai][bj][m][0], v1 = acc[ai][bj][m][1];
;                         u32x4 w;
;                         w.x = cvt_pk_bf16((v0[0] * cc[0] - v0[1] * ss[0]) * s_, (v0[0] * ss[0] + v0[1] * cc[0]) * s_);
;                         w.y = cvt_pk_bf16((v0[2] * cc[1] - v0[3] * ss[1]) * s_, (v0[2] * ss[1] + v0[3] * cc[1]) * s_);
;                         w.z = cvt_pk_bf16((v1[0] * cc[2] - v1[1] * ss[2]) * s_, (v1[0] * ss[2] + v1[1] * cc[2]) * s_);
;                         w.w = cvt_pk_bf16((v1[2] * cc[3] - v1[3] * ss[3]) * s_, (v1[2] * ss[3] + v1[3] * cc[3]) * s_);
;                         *(u32x4*)(rowp + bj * HALF) = w;
.LBB0_571:
	v_or_b32_e32 v114, 16, v210
	v_mov_b64_e32 v[112:113], s[64:65]
	v_mad_i64_i32 v[112:113], s[16:17], v114, s47, v[112:113]
	v_mov_b32_e32 v114, v144
	v_mov_b32_e32 v115, v148
	s_waitcnt lgkmcnt(0)
	v_pk_mul_f32 v[116:117], v[108:109], v[114:115]
	v_mov_b32_e32 v120, v150
	v_sub_f32_e32 v116, v116, v117
	v_mul_f32_e32 v118, v215, v116
	v_mov_b32_e32 v116, v148
	v_mov_b32_e32 v117, v144
	v_pk_mul_f32 v[108:109], v[108:109], v[116:117]
	v_mov_b32_e32 v148, v145
	v_add_f32_e32 v108, v109, v108
	v_mul_f32_e32 v108, v215, v108
	v_mov_b32_e32 v144, v149
	v_cvt_pk_bf16_f32 v108, v118, v108
	v_pk_mul_f32 v[118:119], v[110:111], v[148:149]
	v_pk_mul_f32 v[110:111], v[110:111], v[144:145]
	v_sub_f32_e32 v109, v118, v119
	v_add_f32_e32 v110, v111, v110
	v_mul_f32_e32 v109, v215, v109
	v_mul_f32_e32 v110, v215, v110
	v_mov_b32_e32 v118, v146
	v_mov_b32_e32 v119, v150
	v_mov_b32_e32 v121, v146
	v_cvt_pk_bf16_f32 v109, v109, v110
	v_pk_mul_f32 v[110:111], v[104:105], v[118:119]
	v_pk_mul_f32 v[104:105], v[104:105], v[120:121]
	v_sub_f32_e32 v110, v110, v111
	v_add_f32_e32 v104, v105, v104
	v_mul_f32_e32 v110, v215, v110
	v_mul_f32_e32 v104, v215, v104
	v_mov_b32_e32 v150, v147
	v_cvt_pk_bf16_f32 v110, v110, v104
	v_pk_mul_f32 v[104:105], v[106:107], v[150:151]
	v_mov_b32_e32 v146, v151
	v_sub_f32_e32 v104, v104, v105
	v_mul_f32_e32 v111, v215, v104
	v_pk_mul_f32 v[104:105], v[106:107], v[146:147]
	v_ashrrev_i32_e32 v122, 31, v210
	v_lshl_add_u64 v[112:113], v[162:163], 1, v[112:113]
	v_add_f32_e32 v104, v105, v104
	s_and_b64 vcc, exec, s[6:7]
	v_mul_f32_e32 v104, v215, v104
	v_cvt_pk_bf16_f32 v111, v111, v104
	global_store_dwordx4 v[112:113], v[108:111], off nt
	s_cbranch_vccnz .LBB0_589
	v_cmp_lt_i32_e32 vcc, v228, v222
	s_nop 1
	v_cndmask_b32_e32 v104, v221, v228, vcc
	v_lshlrev_b32_e32 v106, 2, v104
	ds_bpermute_b32 v104, v106, v108
	s_and_saveexec_b64 s[16:17], s[2:3]
	s_xor_b64 s[16:17], exec, s[16:17]
	s_cbranch_execz .LBB0_574
	s_waitcnt lgkmcnt(0)
	v_lshrrev_b32_e32 v104, 16, v104
	v_and_or_b32 v107, v108, s60, v104

; __device__ __forceinline__ unsigned cvt_pk_bf16(float lo, float hi) { unsigned r; asm volatile("v_cvt_pk_bf16_f32 %0, %1, %2" : "=v"(r) : "v"(lo), "v"(hi)); return r; }
;     __device__ __forceinline__ void operator()(const f32x4 (&acc)[2][2][4][2], const Unit& u, int wr, int wc, int fr, int fq) const {
;     ...
;                         const float s_ = sc[m][bj]; const f32x4 cc = c4[m], ss = s4[m];
;                         const f32x4 v0 = acc[ai][bj][m][0], v1 = acc[ai][bj][m][1];
;                         u32x4 w;
;                         w.x = cvt_pk_bf16((v0[0] * cc[0] - v0[1] * ss[0]) * s_, (v0[0] * ss[0] + v0[1] * cc[0]) * s_);
;                         w.y = cvt_pk_bf16((v0[2] * cc[1] - v0[3] * ss[1]) * s_, (v0[2] * ss[1] + v0[3] * cc[1]) * s_);
;                         w.z = cvt_pk_bf16((v1[0] * cc[2] - v1[1] * ss[2]) * s_, (v1[0] * ss[2] + v1[1] * cc[2]) * s_);
;                         w.w = cvt_pk_bf16((v1[2] * cc[3] - v1[3] * ss[3]) * s_, (v1[2] * ss[3] + v1[3] * cc[3]) * s_);
;                         *(u32x4*)(rowp + bj * HALF) = w;
.LBB0_589:
	v_pk_mul_f32 v[104:105], v[100:101], v[114:115]
	v_pk_mul_f32 v[100:101], v[100:101], v[116:117]
	v_sub_f32_e32 v104, v104, v105
	v_add_f32_e32 v100, v101, v100
	v_mul_f32_e32 v104, v214, v104
	v_mul_f32_e32 v100, v214, v100
	v_cvt_pk_bf16_f32 v100, v104, v100
	v_pk_mul_f32 v[104:105], v[102:103], v[148:149]
	v_pk_mul_f32 v[102:103], v[102:103], v[144:145]
	v_sub_f32_e32 v101, v104, v105
	v_add_f32_e32 v102, v103, v102
	v_mul_f32_e32 v101, v214, v101
	v_mul_f32_e32 v102, v214, v102
	v_cvt_pk_bf16_f32 v101, v101, v102
	v_pk_mul_f32 v[102:103], v[96:97], v[118:119]
	v_pk_mul_f32 v[96:97], v[96:97], v[120:121]
	v_sub_f32_e32 v102, v102, v103
	v_add_f32_e32 v96, v97, v96
	v_mul_f32_e32 v102, v214, v102
	v_mul_f32_e32 v96, v214, v96
	v_cvt_pk_bf16_f32 v102, v102, v96
	v_pk_mul_f32 v[96:97], v[98:99], v[150:151]
	s_and_b64 vcc, exec, s[6:7]
	v_sub_f32_e32 v96, v96, v97
	v_mul_f32_e32 v103, v214, v96
	v_pk_mul_f32 v[96:97], v[98:99], v[146:147]
	s_nop 0
	v_add_f32_e32 v96, v97, v96
	v_mul_f32_e32 v96, v214, v96
	v_cvt_pk_bf16_f32 v103, v103, v96
	global_store_dwordx4 v[112:113], v[100:103], off offset:256 nt
	s_cbranch_vccnz .LBB0_607
	v_cmp_lt_i32_e32 vcc, v228, v222
	s_nop 1
	v_cndmask_b32_e32 v96, v221, v228, vcc
	v_lshlrev_b32_e32 v98, 2, v96
	ds_bpermute_b32 v96, v98, v100
	s_and_saveexec_b64 s[16:17], s[2:3]
	s_xor_b64 s[16:17], exec, s[16:17]
	s_cbranch_execz .LBB0_592
	s_waitcnt lgkmcnt(0)
	v_lshrrev_b32_e32 v96, 16, v96
	v_and_or_b32 v99, v100, s60, v96

; __device__ __forceinline__ unsigned cvt_pk_bf16(float lo, float hi) { unsigned r; asm volatile("v_cvt_pk_bf16_f32 %0, %1, %2" : "=v"(r) : "v"(lo), "v"(hi)); return r; }
;     __device__ __forceinline__ void operator()(const f32x4 (&acc)[2][2][4][2], const Unit& u, int wr, int wc, int fr, int fq) const {
;     ...
;                 for (int m = 0; m < 4; ++m) { bf16_t* rowp = O + (size_t)(row0 + ai * HALF + m * 16) * 3072 + col0;
; #pragma unroll
;                     for (int bj = 0; bj < 2; ++bj) {
;                         const float s_ = sc[m][bj]; const f32x4 cc = c4[m], ss = s4[m];
;                         const f32x4 v0 = acc[ai][bj][m][0], v1 = acc[ai][bj][m][1];
;                         u32x4 w;
;                         w.x = cvt_pk_bf16((v0[0] * cc[0] - v0[1] * ss[0]) * s_, (v0[0] * ss[0] + v0[1] * cc[0]) * s_);
;                         w.y = cvt_pk_bf16((v0[2] * cc[1] - v0[3] * ss[1]) * s_, (v0[2] * ss[1] + v0[3] * cc[1]) * s_);
;                         w.z = cvt_pk_bf16((v1[0] * cc[2] - v1[1] * ss[2]) * s_, (v1[0] * ss[2] + v1[1] * cc[2]) * s_);
;                         w.w = cvt_pk_bf16((v1[2] * cc[3] - v1[3] * ss[3]) * s_, (v1[2] * ss[3] + v1[3] * cc[3]) * s_);
;                         *(u32x4*)(rowp + bj * HALF) = w;
.LBB0_607:
	v_or_b32_e32 v98, 32, v210
	v_mov_b64_e32 v[96:97], s[64:65]
	v_mad_i64_i32 v[96:97], s[16:17], v98, s47, v[96:97]
	v_mov_b32_e32 v98, v136
	v_mov_b32_e32 v99, v140
	s_waitcnt lgkmcnt(0)
	v_pk_mul_f32 v[100:101], v[92:93], v[98:99]
	v_mov_b32_e32 v104, v142
	v_sub_f32_e32 v100, v100, v101
	v_mul_f32_e32 v102, v213, v100
	v_mov_b32_e32 v100, v140
	v_mov_b32_e32 v101, v136
	v_pk_mul_f32 v[92:93], v[92:93], v[100:101]
	v_mov_b32_e32 v140, v137
	v_add_f32_e32 v92, v93, v92
	v_mul_f32_e32 v92, v213, v92
	v_mov_b32_e32 v136, v141
	v_cvt_pk_bf16_f32 v92, v102, v92
	v_pk_mul_f32 v[102:103], v[94:95], v[140:141]
	v_pk_mul_f32 v[94:95], v[94:95], v[136:137]
	v_sub_f32_e32 v93, v102, v103
	v_add_f32_e32 v94, v95, v94
	v_mul_f32_e32 v93, v213, v93
	v_mul_f32_e32 v94, v213, v94
	v_mov_b32_e32 v102, v138
	v_mov_b32_e32 v103, v142
	v_mov_b32_e32 v105, v138
	v_cvt_pk_bf16_f32 v93, v93, v94
	v_pk_mul_f32 v[94:95], v[88:89], v[102:103]
	v_pk_mul_f32 v[88:89], v[88:89], v[104:105]
	v_sub_f32_e32 v94, v94, v95
	v_add_f32_e32 v88, v89, v88
	v_mul_f32_e32 v94, v213, v94
	v_mul_f32_e32 v88, v213, v88
	v_mov_b32_e32 v142, v139
	v_cvt_pk_bf16_f32 v94, v94, v88
	v_pk_mul_f32 v[88:89], v[90:91], v[142:143]
	v_mov_b32_e32 v138, v143
	v_sub_f32_e32 v88, v88, v89
	v_mul_f32_e32 v95, v213, v88
	v_pk_mul_f32 v[88:89], v[90:91], v[138:139]
	v_lshl_add_u64 v[96:97], v[162:163], 1, v[96:97]
	v_add_f32_e32 v88, v89, v88
	s_and_b64 vcc, exec, s[6:7]
	v_mul_f32_e32 v88, v213, v88
	v_cvt_pk_bf16_f32 v95, v95, v88
	global_store_dwordx4 v[96:97], v[92:95], off nt
	s_cbranch_vccnz .LBB0_625
	v_cmp_lt_i32_e32 vcc, v228, v222
	s_nop 1
	v_cndmask_b32_e32 v88, v221, v228, vcc
	v_lshlrev_b32_e32 v90, 2, v88
	ds_bpermute_b32 v88, v90, v92
	s_and_saveexec_b64 s[16:17], s[2:3]
	s_xor_b64 s[16:17], exec, s[16:17]
	s_cbranch_execz .LBB0_610
	s_waitcnt lgkmcnt(0)
	v_lshrrev_b32_e32 v88, 16, v88
	v_and_or_b32 v91, v92, s60, v88

; __device__ __forceinline__ unsigned cvt_pk_bf16(float lo, float hi) { unsigned r; asm volatile("v_cvt_pk_bf16_f32 %0, %1, %2" : "=v"(r) : "v"(lo), "v"(hi)); return r; }
;     __device__ __forceinline__ void operator()(const f32x4 (&acc)[2][2][4][2], const Unit& u, int wr, int wc, int fr, int fq) const {
;     ...
;                         const float s_ = sc[m][bj]; const f32x4 cc = c4[m], ss = s4[m];
;                         const f32x4 v0 = acc[ai][bj][m][0], v1 = acc[ai][bj][m][1];
;                         u32x4 w;
;                         w.x = cvt_pk_bf16((v0[0] * cc[0] - v0[1] * ss[0]) * s_, (v0[0] * ss[0] + v0[1] * cc[0]) * s_);
;                         w.y = cvt_pk_bf16((v0[2] * cc[1] - v0[3] * ss[1]) * s_, (v0[2] * ss[1] + v0[3] * cc[1]) * s_);
;                         w.z = cvt_pk_bf16((v1[0] * cc[2] - v1[1] * ss[2]) * s_, (v1[0] * ss[2] + v1[1] * cc[2]) * s_);
;                         w.w = cvt_pk_bf16((v1[2] * cc[3] - v1[3] * ss[3]) * s_, (v1[2] * ss[3] + v1[3] * cc[3]) * s_);
;                         *(u32x4*)(rowp + bj * HALF) = w;
.LBB0_625:
	v_pk_mul_f32 v[88:89], v[84:85], v[98:99]
	v_pk_mul_f32 v[84:85], v[84:85], v[100:101]
	v_sub_f32_e32 v88, v88, v89
	v_add_f32_e32 v84, v85, v84
	v_mul_f32_e32 v88, v212, v88
	v_mul_f32_e32 v84, v212, v84
	v_cvt_pk_bf16_f32 v84, v88, v84
	v_pk_mul_f32 v[88:89], v[86:87], v[140:141]
	v_pk_mul_f32 v[86:87], v[86:87], v[136:137]
	v_sub_f32_e32 v85, v88, v89
	v_add_f32_e32 v86, v87, v86
	v_mul_f32_e32 v85, v212, v85
	v_mul_f32_e32 v86, v212, v86
	v_cvt_pk_bf16_f32 v85, v85, v86
	v_pk_mul_f32 v[86:87], v[80:81], v[102:103]
	v_pk_mul_f32 v[80:81], v[80:81], v[104:105]
	v_sub_f32_e32 v86, v86, v87
	v_add_f32_e32 v80, v81, v80
	v_mul_f32_e32 v86, v212, v86
	v_mul_f32_e32 v80, v212, v80
	v_cvt_pk_bf16_f32 v86, v86, v80
	v_pk_mul_f32 v[80:81], v[82:83], v[142:143]
	s_and_b64 vcc, exec, s[6:7]
	v_sub_f32_e32 v80, v80, v81
	v_mul_f32_e32 v87, v212, v80
	v_pk_mul_f32 v[80:81], v[82:83], v[138:139]
	s_nop 0
	v_add_f32_e32 v80, v81, v80
	v_mul_f32_e32 v80, v212, v80
	v_cvt_pk_bf16_f32 v87, v87, v80
	global_store_dwordx4 v[96:97], v[84:87], off offset:256 nt
	s_cbranch_vccnz .LBB0_643
	v_cmp_lt_i32_e32 vcc, v228, v222
	s_nop 1
	v_cndmask_b32_e32 v80, v221, v228, vcc
	v_lshlrev_b32_e32 v82, 2, v80
	ds_bpermute_b32 v80, v82, v84
	s_and_saveexec_b64 s[16:17], s[2:3]
	s_xor_b64 s[16:17], exec, s[16:17]
	s_cbranch_execz .LBB0_628
	s_waitcnt lgkmcnt(0)
	v_lshrrev_b32_e32 v80, 16, v80
	v_and_or_b32 v83, v84, s60, v80

; __device__ __forceinline__ unsigned cvt_pk_bf16(float lo, float hi) { unsigned r; asm volatile("v_cvt_pk_bf16_f32 %0, %1, %2" : "=v"(r) : "v"(lo), "v"(hi)); return r; }
;     __device__ __forceinline__ void operator()(const f32x4 (&acc)[2][2][4][2], const Unit& u, int wr, int wc, int fr, int fq) const {
;     ...
;                 for (int m = 0; m < 4; ++m) { bf16_t* rowp = O + (size_t)(row0 + ai * HALF + m * 16) * 3072 + col0;
; #pragma unroll
;                     for (int bj = 0; bj < 2; ++bj) {
;                         const float s_ = sc[m][bj]; const f32x4 cc = c4[m], ss = s4[m];
;                         const f32x4 v0 = acc[ai][bj][m][0], v1 = acc[ai][bj][m][1];
;                         u32x4 w;
;                         w.x = cvt_pk_bf16((v0[0] * cc[0] - v0[1] * ss[0]) * s_, (v0[0] * ss[0] + v0[1] * cc[0]) * s_);
;                         w.y = cvt_pk_bf16((v0[2] * cc[1] - v0[3] * ss[1]) * s_, (v0[2] * ss[1] + v0[3] * cc[1]) * s_);
;                         w.z = cvt_pk_bf16((v1[0] * cc[2] - v1[1] * ss[2]) * s_, (v1[0] * ss[2] + v1[1] * cc[2]) * s_);
;                         w.w = cvt_pk_bf16((v1[2] * cc[3] - v1[3] * ss[3]) * s_, (v1[2] * ss[3] + v1[3] * cc[3]) * s_);
;                         *(u32x4*)(rowp + bj * HALF) = w;
.LBB0_643:
	v_or_b32_e32 v82, 48, v210
	v_mov_b64_e32 v[80:81], s[64:65]
	v_mad_i64_i32 v[80:81], s[16:17], v82, s47, v[80:81]
	v_mov_b32_e32 v82, v128
	v_mov_b32_e32 v83, v132
	s_waitcnt lgkmcnt(0)
	v_pk_mul_f32 v[84:85], v[76:77], v[82:83]
	v_mov_b32_e32 v88, v134
	v_sub_f32_e32 v84, v84, v85
	v_mul_f32_e32 v86, v211, v84
	v_mov_b32_e32 v84, v132
	v_mov_b32_e32 v85, v128
	v_pk_mul_f32 v[76:77], v[76:77], v[84:85]
	v_mov_b32_e32 v132, v129
	v_add_f32_e32 v76, v77, v76
	v_mul_f32_e32 v76, v211, v76
	v_mov_b32_e32 v128, v133
	v_cvt_pk_bf16_f32 v76, v86, v76
	v_pk_mul_f32 v[86:87], v[78:79], v[132:133]
	v_pk_mul_f32 v[78:79], v[78:79], v[128:129]
	v_sub_f32_e32 v77, v86, v87
	v_add_f32_e32 v78, v79, v78
	v_mul_f32_e32 v77, v211, v77
	v_mul_f32_e32 v78, v211, v78
	v_mov_b32_e32 v86, v130
	v_mov_b32_e32 v87, v134
	v_mov_b32_e32 v89, v130
	v_cvt_pk_bf16_f32 v77, v77, v78
	v_pk_mul_f32 v[78:79], v[72:73], v[86:87]
	v_pk_mul_f32 v[72:73], v[72:73], v[88:89]
	v_sub_f32_e32 v78, v78, v79
	v_add_f32_e32 v72, v73, v72
	v_mul_f32_e32 v78, v211, v78
	v_mul_f32_e32 v72, v211, v72
	v_mov_b32_e32 v134, v131
	v_cvt_pk_bf16_f32 v78, v78, v72
	v_pk_mul_f32 v[72:73], v[74:75], v[134:135]
	v_mov_b32_e32 v130, v135
	v_sub_f32_e32 v72, v72, v73
	v_mul_f32_e32 v79, v211, v72
	v_pk_mul_f32 v[72:73], v[74:75], v[130:131]
	v_lshl_add_u64 v[80:81], v[162:163], 1, v[80:81]
	v_add_f32_e32 v72, v73, v72
	s_and_b64 vcc, exec, s[6:7]
	v_mul_f32_e32 v72, v211, v72
	v_cvt_pk_bf16_f32 v79, v79, v72
	global_store_dwordx4 v[80:81], v[76:79], off nt
	s_cbranch_vccnz .LBB0_661
	v_cmp_lt_i32_e32 vcc, v228, v222
	s_nop 1
	v_cndmask_b32_e32 v72, v221, v228, vcc
	v_lshlrev_b32_e32 v74, 2, v72
	ds_bpermute_b32 v72, v74, v76
	s_and_saveexec_b64 s[16:17], s[2:3]
	s_xor_b64 s[16:17], exec, s[16:17]
	s_cbranch_execz .LBB0_646
	s_waitcnt lgkmcnt(0)
	v_lshrrev_b32_e32 v72, 16, v72
	v_and_or_b32 v75, v76, s60, v72

; __device__ __forceinline__ unsigned cvt_pk_bf16(float lo, float hi) { unsigned r; asm volatile("v_cvt_pk_bf16_f32 %0, %1, %2" : "=v"(r) : "v"(lo), "v"(hi)); return r; }
;     __device__ __forceinline__ void operator()(const f32x4 (&acc)[2][2][4][2], const Unit& u, int wr, int wc, int fr, int fq) const {
;     ...
;                         const float s_ = sc[m][bj]; const f32x4 cc = c4[m], ss = s4[m];
;                         const f32x4 v0 = acc[ai][bj][m][0], v1 = acc[ai][bj][m][1];
;                         u32x4 w;
;                         w.x = cvt_pk_bf16((v0[0] * cc[0] - v0[1] * ss[0]) * s_, (v0[0] * ss[0] + v0[1] * cc[0]) * s_);
;                         w.y = cvt_pk_bf16((v0[2] * cc[1] - v0[3] * ss[1]) * s_, (v0[2] * ss[1] + v0[3] * cc[1]) * s_);
;                         w.z = cvt_pk_bf16((v1[0] * cc[2] - v1[1] * ss[2]) * s_, (v1[0] * ss[2] + v1[1] * cc[2]) * s_);
;                         w.w = cvt_pk_bf16((v1[2] * cc[3] - v1[3] * ss[3]) * s_, (v1[2] * ss[3] + v1[3] * cc[3]) * s_);
;                         *(u32x4*)(rowp + bj * HALF) = w;
.LBB0_661:
	v_pk_mul_f32 v[72:73], v[68:69], v[82:83]
	v_pk_mul_f32 v[68:69], v[68:69], v[84:85]
	v_sub_f32_e32 v72, v72, v73
	v_add_f32_e32 v68, v69, v68
	v_mul_f32_e32 v72, v187, v72
	v_mul_f32_e32 v68, v187, v68
	v_cvt_pk_bf16_f32 v68, v72, v68
	v_pk_mul_f32 v[72:73], v[70:71], v[132:133]
	v_pk_mul_f32 v[70:71], v[70:71], v[128:129]
	v_sub_f32_e32 v69, v72, v73
	v_add_f32_e32 v70, v71, v70
	v_mul_f32_e32 v69, v187, v69
	v_mul_f32_e32 v70, v187, v70
	v_cvt_pk_bf16_f32 v69, v69, v70
	v_pk_mul_f32 v[70:71], v[64:65], v[86:87]
	v_pk_mul_f32 v[64:65], v[64:65], v[88:89]
	v_sub_f32_e32 v70, v70, v71
	v_add_f32_e32 v64, v65, v64
	v_mul_f32_e32 v70, v187, v70
	v_mul_f32_e32 v64, v187, v64
	v_cvt_pk_bf16_f32 v70, v70, v64
	v_pk_mul_f32 v[64:65], v[66:67], v[134:135]
	s_and_b64 vcc, exec, s[6:7]
	v_sub_f32_e32 v64, v64, v65
	v_mul_f32_e32 v71, v187, v64
	v_pk_mul_f32 v[64:65], v[66:67], v[130:131]
	s_nop 0
	v_add_f32_e32 v64, v65, v64
	v_mul_f32_e32 v64, v187, v64
	v_cvt_pk_bf16_f32 v71, v71, v64
	global_store_dwordx4 v[80:81], v[68:71], off offset:256 nt
	s_cbranch_vccnz .LBB0_679
	v_cmp_lt_i32_e32 vcc, v228, v222
	s_nop 1
	v_cndmask_b32_e32 v64, v221, v228, vcc
	v_lshlrev_b32_e32 v66, 2, v64
	ds_bpermute_b32 v64, v66, v68
	s_and_saveexec_b64 s[16:17], s[2:3]
	s_xor_b64 s[16:17], exec, s[16:17]
	s_cbranch_execz .LBB0_664
	s_waitcnt lgkmcnt(0)
	v_lshrrev_b32_e32 v64, 16, v64
	v_and_or_b32 v67, v68, s60, v64

; __device__ __forceinline__ unsigned cvt_pk_bf16(float lo, float hi) { unsigned r; asm volatile("v_cvt_pk_bf16_f32 %0, %1, %2" : "=v"(r) : "v"(lo), "v"(hi)); return r; }
;     __device__ __forceinline__ void operator()(const f32x4 (&acc)[2][2][4][2], const Unit& u, int wr, int wc, int fr, int fq) const {
;     ...
;                 for (int m = 0; m < 4; ++m) { const int row = row0 + ai * HALF + m * 16, t = row & 4095, p = t & 127;
;                     c4[m] = *(const f32x4*)(cs + t * 64 + 16 * wc + 4 * fq); s4[m] = *(const f32x4*)(sn + t * 64 + 16 * wc + 4 * fq);
;                     sc[m][0] = dtab[hb * 128 + p]; sc[m][1] = dtab[(hb + 1) * 128 + p]; }
;                 __builtin_amdgcn_sched_barrier(0);
; #pragma unroll
;                 for (int m = 0; m < 4; ++m) { bf16_t* rowp = O + (size_t)(row0 + ai * HALF + m * 16) * 3072 + col0;
; #pragma unroll
;                     for (int bj = 0; bj < 2; ++bj) {
;                         const float s_ = sc[m][bj]; const f32x4 cc = c4[m], ss = s4[m];
;                         const f32x4 v0 = acc[ai][bj][m][0], v1 = acc[ai][bj][m][1];
;                         u32x4 w;
;                         w.x = cvt_pk_bf16((v0[0] * cc[0] - v0[1] * ss[0]) * s_, (v0[0] * ss[0] + v0[1] * cc[0]) * s_);
;                         w.y = cvt_pk_bf16((v0[2] * cc[1] - v0[3] * ss[1]) * s_, (v0[2] * ss[1] + v0[3] * cc[1]) * s_);
;                         w.z = cvt_pk_bf16((v1[0] * cc[2] - v1[1] * ss[2]) * s_, (v1[0] * ss[2] + v1[1] * cc[2]) * s_);
;                         w.w = cvt_pk_bf16((v1[2] * cc[3] - v1[3] * ss[3]) * s_, (v1[2] * ss[3] + v1[3] * cc[3]) * s_);
;                         *(u32x4*)(rowp + bj * HALF) = w;
.LBB0_679:
	v_mov_b32_e32 v187, v163
	v_lshl_add_u64 v[64:65], s[78:79], 0, v[186:187]
	v_add_u32_e32 v98, 0x80, v210
	v_and_b32_e32 v70, 0xfcf, v98
	v_lshlrev_b32_e32 v66, 8, v70
	v_mov_b32_e32 v67, v163
	s_waitcnt lgkmcnt(0)
	v_lshl_add_u64 v[68:69], v[178:179], 0, v[66:67]
	v_lshl_add_u64 v[66:67], v[180:181], 0, v[66:67]
	global_load_dwordx4 v[88:91], v[68:69], off
	global_load_dwordx4 v[92:95], v[66:67], off
	global_load_dword v113, v[64:65], off
	global_load_dword v112, v[64:65], off offset:512
	v_or_b32_e32 v64, 16, v70
	s_movk_i32 s16, 0x5f
	v_lshlrev_b32_e32 v64, 8, v64
	v_mov_b32_e32 v65, v163
	v_bitop3_b32 v68, v70, s16, 16 bitop3:0xc8
	v_lshl_add_u64 v[66:67], v[178:179], 0, v[64:65]
	v_lshl_add_u64 v[64:65], v[180:181], 0, v[64:65]
	global_load_dwordx4 v[80:83], v[66:67], off
	global_load_dwordx4 v[84:87], v[64:65], off
	v_or_b32_e32 v64, s71, v68
	v_lshlrev_b32_e32 v64, 2, v64
	global_load_dword v111, v64, s[78:79]
	global_load_dword v110, v64, s[78:79] offset:512
	v_or_b32_e32 v64, 32, v70
	s_movk_i32 s16, 0x6f
	v_lshlrev_b32_e32 v64, 8, v64
	v_mov_b32_e32 v65, v163
	v_bitop3_b32 v68, v70, s16, 32 bitop3:0xc8
	v_lshl_add_u64 v[66:67], v[178:179], 0, v[64:65]
	v_lshl_add_u64 v[64:65], v[180:181], 0, v[64:65]
	global_load_dwordx4 v[72:75], v[66:67], off
	global_load_dwordx4 v[76:79], v[64:65], off
	v_or_b32_e32 v64, s71, v68
	v_lshlrev_b32_e32 v64, 2, v64
	s_movk_i32 s16, 0x7f
	global_load_dword v109, v64, s[78:79]
	global_load_dword v108, v64, s[78:79] offset:512
	v_or_b32_e32 v64, 48, v70
	v_bitop3_b32 v96, v70, s16, 48 bitop3:0xc8
	v_lshlrev_b32_e32 v64, 8, v64
	v_mov_b32_e32 v65, v163
	v_or_b32_e32 v96, s71, v96
	v_lshl_add_u64 v[66:67], v[178:179], 0, v[64:65]
	v_lshl_add_u64 v[68:69], v[180:181], 0, v[64:65]
	v_lshlrev_b32_e32 v96, 2, v96
	global_load_dwordx4 v[64:67], v[66:67], off
	s_nop 0
	global_load_dwordx4 v[68:71], v[68:69], off
	s_nop 0
	global_load_dword v107, v96, s[78:79]
	global_load_dword v106, v96, s[78:79] offset:512
	v_mov_b64_e32 v[96:97], s[64:65]
	v_mad_i64_i32 v[96:97], s[16:17], v98, s47, v[96:97]
	s_waitcnt vmcnt(15)
	v_mov_b32_e32 v98, v88
	s_waitcnt vmcnt(14)
	v_mov_b32_e32 v99, v92
	v_pk_mul_f32 v[100:101], v[60:61], v[98:99]
	v_mov_b32_e32 v104, v94
	v_sub_f32_e32 v100, v100, v101
	s_waitcnt vmcnt(13)
	v_mul_f32_e32 v102, v113, v100
	v_mov_b32_e32 v100, v92
	v_mov_b32_e32 v101, v88
	v_pk_mul_f32 v[60:61], v[60:61], v[100:101]
	v_mov_b32_e32 v92, v89
	v_add_f32_e32 v60, v61, v60
	v_mul_f32_e32 v60, v113, v60
	v_mov_b32_e32 v88, v93
	v_cvt_pk_bf16_f32 v60, v102, v60
	v_pk_mul_f32 v[102:103], v[62:63], v[92:93]
	v_pk_mul_f32 v[62:63], v[62:63], v[88:89]
	v_sub_f32_e32 v61, v102, v103
	v_add_f32_e32 v62, v63, v62
	v_mul_f32_e32 v61, v113, v61
	v_mul_f32_e32 v62, v113, v62
	v_mov_b32_e32 v102, v90
	v_mov_b32_e32 v103, v94
	v_mov_b32_e32 v105, v90
	v_cvt_pk_bf16_f32 v61, v61, v62
	v_pk_mul_f32 v[62:63], v[56:57], v[102:103]
	v_pk_mul_f32 v[56:57], v[56:57], v[104:105]
	v_sub_f32_e32 v62, v62, v63
	v_add_f32_e32 v56, v57, v56
	v_mul_f32_e32 v62, v113, v62
	v_mul_f32_e32 v56, v113, v56
	v_mov_b32_e32 v94, v91
	v_cvt_pk_bf16_f32 v62, v62, v56
	v_pk_mul_f32 v[56:57], v[58:59], v[94:95]
	v_mov_b32_e32 v90, v95
	v_sub_f32_e32 v56, v56, v57
	v_mul_f32_e32 v63, v113, v56
	v_pk_mul_f32 v[56:57], v[58:59], v[90:91]
	v_lshl_add_u64 v[96:97], v[162:163], 1, v[96:97]
	v_add_f32_e32 v56, v57, v56
	s_and_b64 vcc, exec, s[6:7]
	v_mul_f32_e32 v56, v113, v56
	v_cvt_pk_bf16_f32 v63, v63, v56
	global_store_dwordx4 v[96:97], v[60:63], off nt
	s_cbranch_vccnz .LBB0_697
	v_cmp_lt_i32_e32 vcc, v228, v222
	s_nop 1
	v_cndmask_b32_e32 v56, v221, v228, vcc
	v_lshlrev_b32_e32 v58, 2, v56
	ds_bpermute_b32 v56, v58, v60
	s_and_saveexec_b64 s[16:17], s[2:3]
	s_xor_b64 s[16:17], exec, s[16:17]
	s_cbranch_execz .LBB0_682
	s_waitcnt lgkmcnt(0)
	v_lshrrev_b32_e32 v56, 16, v56
	v_and_or_b32 v59, v60, s60, v56

; __device__ __forceinline__ unsigned cvt_pk_bf16(float lo, float hi) { unsigned r; asm volatile("v_cvt_pk_bf16_f32 %0, %1, %2" : "=v"(r) : "v"(lo), "v"(hi)); return r; }
;     __device__ __forceinline__ void operator()(const f32x4 (&acc)[2][2][4][2], const Unit& u, int wr, int wc, int fr, int fq) const {
;     ...
;                         const float s_ = sc[m][bj]; const f32x4 cc = c4[m], ss = s4[m];
;                         const f32x4 v0 = acc[ai][bj][m][0], v1 = acc[ai][bj][m][1];
;                         u32x4 w;
;                         w.x = cvt_pk_bf16((v0[0] * cc[0] - v0[1] * ss[0]) * s_, (v0[0] * ss[0] + v0[1] * cc[0]) * s_);
;                         w.y = cvt_pk_bf16((v0[2] * cc[1] - v0[3] * ss[1]) * s_, (v0[2] * ss[1] + v0[3] * cc[1]) * s_);
;                         w.z = cvt_pk_bf16((v1[0] * cc[2] - v1[1] * ss[2]) * s_, (v1[0] * ss[2] + v1[1] * cc[2]) * s_);
;                         w.w = cvt_pk_bf16((v1[2] * cc[3] - v1[3] * ss[3]) * s_, (v1[2] * ss[3] + v1[3] * cc[3]) * s_);
;                         *(u32x4*)(rowp + bj * HALF) = w;
.LBB0_697:
	v_pk_mul_f32 v[56:57], v[52:53], v[98:99]
	v_pk_mul_f32 v[52:53], v[52:53], v[100:101]
	v_sub_f32_e32 v56, v56, v57
	v_add_f32_e32 v52, v53, v52
	s_waitcnt vmcnt(13)
	v_mul_f32_e32 v56, v112, v56
	v_mul_f32_e32 v52, v112, v52
	v_cvt_pk_bf16_f32 v52, v56, v52
	v_pk_mul_f32 v[56:57], v[54:55], v[92:93]
	v_pk_mul_f32 v[54:55], v[54:55], v[88:89]
	v_sub_f32_e32 v53, v56, v57
	v_add_f32_e32 v54, v55, v54
	v_mul_f32_e32 v53, v112, v53
	v_mul_f32_e32 v54, v112, v54
	v_cvt_pk_bf16_f32 v53, v53, v54
	v_pk_mul_f32 v[54:55], v[48:49], v[102:103]
	v_pk_mul_f32 v[48:49], v[48:49], v[104:105]
	v_sub_f32_e32 v54, v54, v55
	v_add_f32_e32 v48, v49, v48
	v_mul_f32_e32 v54, v112, v54
	v_mul_f32_e32 v48, v112, v48
	v_cvt_pk_bf16_f32 v54, v54, v48
	v_pk_mul_f32 v[48:49], v[50:51], v[94:95]
	s_and_b64 vcc, exec, s[6:7]
	v_sub_f32_e32 v48, v48, v49
	v_mul_f32_e32 v55, v112, v48
	v_pk_mul_f32 v[48:49], v[50:51], v[90:91]
	s_nop 0
	v_add_f32_e32 v48, v49, v48
	v_mul_f32_e32 v48, v112, v48
	v_cvt_pk_bf16_f32 v55, v55, v48
	global_store_dwordx4 v[96:97], v[52:55], off offset:256 nt
	s_cbranch_vccnz .LBB0_715
	v_cmp_lt_i32_e32 vcc, v228, v222
	s_nop 1
	v_cndmask_b32_e32 v48, v221, v228, vcc
	v_lshlrev_b32_e32 v50, 2, v48
	ds_bpermute_b32 v48, v50, v52
	s_and_saveexec_b64 s[16:17], s[2:3]
	s_xor_b64 s[16:17], exec, s[16:17]
	s_cbranch_execz .LBB0_700
	s_waitcnt lgkmcnt(0)
	v_lshrrev_b32_e32 v48, 16, v48
	v_and_or_b32 v51, v52, s60, v48

; __device__ __forceinline__ unsigned cvt_pk_bf16(float lo, float hi) { unsigned r; asm volatile("v_cvt_pk_bf16_f32 %0, %1, %2" : "=v"(r) : "v"(lo), "v"(hi)); return r; }
;     __device__ __forceinline__ void operator()(const f32x4 (&acc)[2][2][4][2], const Unit& u, int wr, int wc, int fr, int fq) const {
;     ...
;                 for (int m = 0; m < 4; ++m) { bf16_t* rowp = O + (size_t)(row0 + ai * HALF + m * 16) * 3072 + col0;
; #pragma unroll
;                     for (int bj = 0; bj < 2; ++bj) {
;                         const float s_ = sc[m][bj]; const f32x4 cc = c4[m], ss = s4[m];
;                         const f32x4 v0 = acc[ai][bj][m][0], v1 = acc[ai][bj][m][1];
;                         u32x4 w;
;                         w.x = cvt_pk_bf16((v0[0] * cc[0] - v0[1] * ss[0]) * s_, (v0[0] * ss[0] + v0[1] * cc[0]) * s_);
;                         w.y = cvt_pk_bf16((v0[2] * cc[1] - v0[3] * ss[1]) * s_, (v0[2] * ss[1] + v0[3] * cc[1]) * s_);
;                         w.z = cvt_pk_bf16((v1[0] * cc[2] - v1[1] * ss[2]) * s_, (v1[0] * ss[2] + v1[1] * cc[2]) * s_);
;                         w.w = cvt_pk_bf16((v1[2] * cc[3] - v1[3] * ss[3]) * s_, (v1[2] * ss[3] + v1[3] * cc[3]) * s_);
;                         *(u32x4*)(rowp + bj * HALF) = w;
.LBB0_715:
	v_add_u32_e32 v50, 0x90, v210
	v_mov_b64_e32 v[48:49], s[64:65]
	v_mad_i64_i32 v[48:49], s[16:17], v50, s47, v[48:49]
	s_waitcnt vmcnt(13)
	v_mov_b32_e32 v50, v80
	s_waitcnt vmcnt(12)
	v_mov_b32_e32 v51, v84
	s_waitcnt lgkmcnt(0)
	v_pk_mul_f32 v[52:53], v[44:45], v[50:51]
	v_mov_b32_e32 v56, v86
	v_sub_f32_e32 v52, v52, v53
	s_waitcnt vmcnt(11)
	v_mul_f32_e32 v54, v111, v52
	v_mov_b32_e32 v52, v84
	v_mov_b32_e32 v53, v80
	v_pk_mul_f32 v[44:45], v[44:45], v[52:53]
	v_mov_b32_e32 v84, v81
	v_add_f32_e32 v44, v45, v44
	v_mul_f32_e32 v44, v111, v44
	v_mov_b32_e32 v80, v85
	v_cvt_pk_bf16_f32 v44, v54, v44
	v_pk_mul_f32 v[54:55], v[46:47], v[84:85]
	v_pk_mul_f32 v[46:47], v[46:47], v[80:81]
	v_sub_f32_e32 v45, v54, v55
	v_add_f32_e32 v46, v47, v46
	v_mul_f32_e32 v45, v111, v45
	v_mul_f32_e32 v46, v111, v46
	v_mov_b32_e32 v54, v82
	v_mov_b32_e32 v55, v86
	v_mov_b32_e32 v57, v82
	v_cvt_pk_bf16_f32 v45, v45, v46
	v_pk_mul_f32 v[46:47], v[40:41], v[54:55]
	v_pk_mul_f32 v[40:41], v[40:41], v[56:57]
	v_sub_f32_e32 v46, v46, v47
	v_add_f32_e32 v40, v41, v40
	v_mul_f32_e32 v46, v111, v46
	v_mul_f32_e32 v40, v111, v40
	v_mov_b32_e32 v86, v83
	v_cvt_pk_bf16_f32 v46, v46, v40
	v_pk_mul_f32 v[40:41], v[42:43], v[86:87]
	v_mov_b32_e32 v82, v87
	v_sub_f32_e32 v40, v40, v41
	v_mul_f32_e32 v47, v111, v40
	v_pk_mul_f32 v[40:41], v[42:43], v[82:83]
	v_lshl_add_u64 v[48:49], v[162:163], 1, v[48:49]
	v_add_f32_e32 v40, v41, v40
	s_and_b64 vcc, exec, s[6:7]
	v_mul_f32_e32 v40, v111, v40
	v_cvt_pk_bf16_f32 v47, v47, v40
	global_store_dwordx4 v[48:49], v[44:47], off nt
	s_cbranch_vccnz .LBB0_733
	v_cmp_lt_i32_e32 vcc, v228, v222
	s_nop 1
	v_cndmask_b32_e32 v40, v221, v228, vcc
	v_lshlrev_b32_e32 v42, 2, v40
	ds_bpermute_b32 v40, v42, v44
	s_and_saveexec_b64 s[16:17], s[2:3]
	s_xor_b64 s[16:17], exec, s[16:17]
	s_cbranch_execz .LBB0_718
	s_waitcnt lgkmcnt(0)
	v_lshrrev_b32_e32 v40, 16, v40
	v_and_or_b32 v43, v44, s60, v40

; __device__ __forceinline__ unsigned cvt_pk_bf16(float lo, float hi) { unsigned r; asm volatile("v_cvt_pk_bf16_f32 %0, %1, %2" : "=v"(r) : "v"(lo), "v"(hi)); return r; }
;     __device__ __forceinline__ void operator()(const f32x4 (&acc)[2][2][4][2], const Unit& u, int wr, int wc, int fr, int fq) const {
;     ...
;                         const float s_ = sc[m][bj]; const f32x4 cc = c4[m], ss = s4[m];
;                         const f32x4 v0 = acc[ai][bj][m][0], v1 = acc[ai][bj][m][1];
;                         u32x4 w;
;                         w.x = cvt_pk_bf16((v0[0] * cc[0] - v0[1] * ss[0]) * s_, (v0[0] * ss[0] + v0[1] * cc[0]) * s_);
;                         w.y = cvt_pk_bf16((v0[2] * cc[1] - v0[3] * ss[1]) * s_, (v0[2] * ss[1] + v0[3] * cc[1]) * s_);
;                         w.z = cvt_pk_bf16((v1[0] * cc[2] - v1[1] * ss[2]) * s_, (v1[0] * ss[2] + v1[1] * cc[2]) * s_);
;                         w.w = cvt_pk_bf16((v1[2] * cc[3] - v1[3] * ss[3]) * s_, (v1[2] * ss[3] + v1[3] * cc[3]) * s_);
;                         *(u32x4*)(rowp + bj * HALF) = w;
.LBB0_733:
	v_pk_mul_f32 v[40:41], v[36:37], v[50:51]
	v_pk_mul_f32 v[36:37], v[36:37], v[52:53]
	v_sub_f32_e32 v40, v40, v41
	v_add_f32_e32 v36, v37, v36
	s_waitcnt vmcnt(11)
	v_mul_f32_e32 v40, v110, v40
	v_mul_f32_e32 v36, v110, v36
	v_cvt_pk_bf16_f32 v36, v40, v36
	v_pk_mul_f32 v[40:41], v[38:39], v[84:85]
	v_pk_mul_f32 v[38:39], v[38:39], v[80:81]
	v_sub_f32_e32 v37, v40, v41
	v_add_f32_e32 v38, v39, v38
	v_mul_f32_e32 v37, v110, v37
	v_mul_f32_e32 v38, v110, v38
	v_cvt_pk_bf16_f32 v37, v37, v38
	v_pk_mul_f32 v[38:39], v[32:33], v[54:55]
	v_pk_mul_f32 v[32:33], v[32:33], v[56:57]
	v_sub_f32_e32 v38, v38, v39
	v_add_f32_e32 v32, v33, v32
	v_mul_f32_e32 v38, v110, v38
	v_mul_f32_e32 v32, v110, v32
	v_cvt_pk_bf16_f32 v38, v38, v32
	v_pk_mul_f32 v[32:33], v[34:35], v[86:87]
	s_and_b64 vcc, exec, s[6:7]
	v_sub_f32_e32 v32, v32, v33
	v_mul_f32_e32 v39, v110, v32
	v_pk_mul_f32 v[32:33], v[34:35], v[82:83]
	s_nop 0
	v_add_f32_e32 v32, v33, v32
	v_mul_f32_e32 v32, v110, v32
	v_cvt_pk_bf16_f32 v39, v39, v32
	global_store_dwordx4 v[48:49], v[36:39], off offset:256 nt
	s_cbranch_vccnz .LBB0_751
	v_cmp_lt_i32_e32 vcc, v228, v222
	s_nop 1
	v_cndmask_b32_e32 v32, v221, v228, vcc
	v_lshlrev_b32_e32 v34, 2, v32
	ds_bpermute_b32 v32, v34, v36
	s_and_saveexec_b64 s[16:17], s[2:3]
	s_xor_b64 s[16:17], exec, s[16:17]
	s_cbranch_execz .LBB0_736
	s_waitcnt lgkmcnt(0)
	v_lshrrev_b32_e32 v32, 16, v32
	v_and_or_b32 v35, v36, s60, v32

; __device__ __forceinline__ unsigned cvt_pk_bf16(float lo, float hi) { unsigned r; asm volatile("v_cvt_pk_bf16_f32 %0, %1, %2" : "=v"(r) : "v"(lo), "v"(hi)); return r; }
;     __device__ __forceinline__ void operator()(const f32x4 (&acc)[2][2][4][2], const Unit& u, int wr, int wc, int fr, int fq) const {
;     ...
;                 for (int m = 0; m < 4; ++m) { bf16_t* rowp = O + (size_t)(row0 + ai * HALF + m * 16) * 3072 + col0;
; #pragma unroll
;                     for (int bj = 0; bj < 2; ++bj) {
;                         const float s_ = sc[m][bj]; const f32x4 cc = c4[m], ss = s4[m];
;                         const f32x4 v0 = acc[ai][bj][m][0], v1 = acc[ai][bj][m][1];
;                         u32x4 w;
;                         w.x = cvt_pk_bf16((v0[0] * cc[0] - v0[1] * ss[0]) * s_, (v0[0] * ss[0] + v0[1] * cc[0]) * s_);
;                         w.y = cvt_pk_bf16((v0[2] * cc[1] - v0[3] * ss[1]) * s_, (v0[2] * ss[1] + v0[3] * cc[1]) * s_);
;                         w.z = cvt_pk_bf16((v1[0] * cc[2] - v1[1] * ss[2]) * s_, (v1[0] * ss[2] + v1[1] * cc[2]) * s_);
;                         w.w = cvt_pk_bf16((v1[2] * cc[3] - v1[3] * ss[3]) * s_, (v1[2] * ss[3] + v1[3] * cc[3]) * s_);
;                         *(u32x4*)(rowp + bj * HALF) = w;
.LBB0_751:
	v_add_u32_e32 v34, 0xa0, v210
	v_mov_b64_e32 v[32:33], s[64:65]
	v_mad_i64_i32 v[32:33], s[16:17], v34, s47, v[32:33]
	s_waitcnt vmcnt(11)
	v_mov_b32_e32 v34, v72
	s_waitcnt vmcnt(10)
	v_mov_b32_e32 v35, v76
	s_waitcnt lgkmcnt(0)
	v_pk_mul_f32 v[36:37], v[28:29], v[34:35]
	v_mov_b32_e32 v40, v78
	v_sub_f32_e32 v36, v36, v37
	s_waitcnt vmcnt(9)
	v_mul_f32_e32 v38, v109, v36
	v_mov_b32_e32 v36, v76
	v_mov_b32_e32 v37, v72
	v_pk_mul_f32 v[28:29], v[28:29], v[36:37]
	v_mov_b32_e32 v76, v73
	v_add_f32_e32 v28, v29, v28
	v_mul_f32_e32 v28, v109, v28
	v_mov_b32_e32 v72, v77
	v_cvt_pk_bf16_f32 v28, v38, v28
	v_pk_mul_f32 v[38:39], v[30:31], v[76:77]
	v_pk_mul_f32 v[30:31], v[30:31], v[72:73]
	v_sub_f32_e32 v29, v38, v39
	v_add_f32_e32 v30, v31, v30
	v_mul_f32_e32 v29, v109, v29
	v_mul_f32_e32 v30, v109, v30
	v_mov_b32_e32 v38, v74
	v_mov_b32_e32 v39, v78
	v_mov_b32_e32 v41, v74
	v_cvt_pk_bf16_f32 v29, v29, v30
	v_pk_mul_f32 v[30:31], v[24:25], v[38:39]
	v_pk_mul_f32 v[24:25], v[24:25], v[40:41]
	v_sub_f32_e32 v30, v30, v31
	v_add_f32_e32 v24, v25, v24
	v_mul_f32_e32 v30, v109, v30
	v_mul_f32_e32 v24, v109, v24
	v_mov_b32_e32 v78, v75
	v_cvt_pk_bf16_f32 v30, v30, v24
	v_pk_mul_f32 v[24:25], v[26:27], v[78:79]
	v_mov_b32_e32 v74, v79
	v_sub_f32_e32 v24, v24, v25
	v_mul_f32_e32 v31, v109, v24
	v_pk_mul_f32 v[24:25], v[26:27], v[74:75]
	v_lshl_add_u64 v[32:33], v[162:163], 1, v[32:33]
	v_add_f32_e32 v24, v25, v24
	s_and_b64 vcc, exec, s[6:7]
	v_mul_f32_e32 v24, v109, v24
	v_cvt_pk_bf16_f32 v31, v31, v24
	global_store_dwordx4 v[32:33], v[28:31], off nt
	s_cbranch_vccnz .LBB0_769
	v_cmp_lt_i32_e32 vcc, v228, v222
	s_nop 1
	v_cndmask_b32_e32 v24, v221, v228, vcc
	v_lshlrev_b32_e32 v26, 2, v24
	ds_bpermute_b32 v24, v26, v28
	s_and_saveexec_b64 s[16:17], s[2:3]
	s_xor_b64 s[16:17], exec, s[16:17]
	s_cbranch_execz .LBB0_754
	s_waitcnt lgkmcnt(0)
	v_lshrrev_b32_e32 v24, 16, v24
	v_and_or_b32 v27, v28, s60, v24

; __device__ __forceinline__ unsigned cvt_pk_bf16(float lo, float hi) { unsigned r; asm volatile("v_cvt_pk_bf16_f32 %0, %1, %2" : "=v"(r) : "v"(lo), "v"(hi)); return r; }
;     __device__ __forceinline__ void operator()(const f32x4 (&acc)[2][2][4][2], const Unit& u, int wr, int wc, int fr, int fq) const {
;     ...
;                         const float s_ = sc[m][bj]; const f32x4 cc = c4[m], ss = s4[m];
;                         const f32x4 v0 = acc[ai][bj][m][0], v1 = acc[ai][bj][m][1];
;                         u32x4 w;
;                         w.x = cvt_pk_bf16((v0[0] * cc[0] - v0[1] * ss[0]) * s_, (v0[0] * ss[0] + v0[1] * cc[0]) * s_);
;                         w.y = cvt_pk_bf16((v0[2] * cc[1] - v0[3] * ss[1]) * s_, (v0[2] * ss[1] + v0[3] * cc[1]) * s_);
;                         w.z = cvt_pk_bf16((v1[0] * cc[2] - v1[1] * ss[2]) * s_, (v1[0] * ss[2] + v1[1] * cc[2]) * s_);
;                         w.w = cvt_pk_bf16((v1[2] * cc[3] - v1[3] * ss[3]) * s_, (v1[2] * ss[3] + v1[3] * cc[3]) * s_);
;                         *(u32x4*)(rowp + bj * HALF) = w;
.LBB0_769:
	v_pk_mul_f32 v[24:25], v[20:21], v[34:35]
	v_pk_mul_f32 v[20:21], v[20:21], v[36:37]
	v_sub_f32_e32 v24, v24, v25
	v_add_f32_e32 v20, v21, v20
	s_waitcnt vmcnt(9)
	v_mul_f32_e32 v24, v108, v24
	v_mul_f32_e32 v20, v108, v20
	v_cvt_pk_bf16_f32 v20, v24, v20
	v_pk_mul_f32 v[24:25], v[22:23], v[76:77]
	v_pk_mul_f32 v[22:23], v[22:23], v[72:73]
	v_sub_f32_e32 v21, v24, v25
	v_add_f32_e32 v22, v23, v22
	v_mul_f32_e32 v21, v108, v21
	v_mul_f32_e32 v22, v108, v22
	v_cvt_pk_bf16_f32 v21, v21, v22
	v_pk_mul_f32 v[22:23], v[16:17], v[38:39]
	v_pk_mul_f32 v[16:17], v[16:17], v[40:41]
	v_sub_f32_e32 v22, v22, v23
	v_add_f32_e32 v16, v17, v16
	v_mul_f32_e32 v22, v108, v22
	v_mul_f32_e32 v16, v108, v16
	v_cvt_pk_bf16_f32 v22, v22, v16
	v_pk_mul_f32 v[16:17], v[18:19], v[78:79]
	s_and_b64 vcc, exec, s[6:7]
	v_sub_f32_e32 v16, v16, v17
	v_mul_f32_e32 v23, v108, v16
	v_pk_mul_f32 v[16:17], v[18:19], v[74:75]
	s_nop 0
	v_add_f32_e32 v16, v17, v16
	v_mul_f32_e32 v16, v108, v16
	v_cvt_pk_bf16_f32 v23, v23, v16
	global_store_dwordx4 v[32:33], v[20:23], off offset:256 nt
	s_cbranch_vccnz .LBB0_787
	v_cmp_lt_i32_e32 vcc, v228, v222
	s_nop 1
	v_cndmask_b32_e32 v16, v221, v228, vcc
	v_lshlrev_b32_e32 v18, 2, v16
	ds_bpermute_b32 v16, v18, v20
	s_and_saveexec_b64 s[16:17], s[2:3]
	s_xor_b64 s[16:17], exec, s[16:17]
	s_cbranch_execz .LBB0_772
	s_waitcnt lgkmcnt(0)
	v_lshrrev_b32_e32 v16, 16, v16
	v_and_or_b32 v19, v20, s60, v16

; __device__ __forceinline__ unsigned cvt_pk_bf16(float lo, float hi) { unsigned r; asm volatile("v_cvt_pk_bf16_f32 %0, %1, %2" : "=v"(r) : "v"(lo), "v"(hi)); return r; }
;     __device__ __forceinline__ void operator()(const f32x4 (&acc)[2][2][4][2], const Unit& u, int wr, int wc, int fr, int fq) const {
;     ...
;                 for (int m = 0; m < 4; ++m) { bf16_t* rowp = O + (size_t)(row0 + ai * HALF + m * 16) * 3072 + col0;
; #pragma unroll
;                     for (int bj = 0; bj < 2; ++bj) {
;                         const float s_ = sc[m][bj]; const f32x4 cc = c4[m], ss = s4[m];
;                         const f32x4 v0 = acc[ai][bj][m][0], v1 = acc[ai][bj][m][1];
;                         u32x4 w;
;                         w.x = cvt_pk_bf16((v0[0] * cc[0] - v0[1] * ss[0]) * s_, (v0[0] * ss[0] + v0[1] * cc[0]) * s_);
;                         w.y = cvt_pk_bf16((v0[2] * cc[1] - v0[3] * ss[1]) * s_, (v0[2] * ss[1] + v0[3] * cc[1]) * s_);
;                         w.z = cvt_pk_bf16((v1[0] * cc[2] - v1[1] * ss[2]) * s_, (v1[0] * ss[2] + v1[1] * cc[2]) * s_);
;                         w.w = cvt_pk_bf16((v1[2] * cc[3] - v1[3] * ss[3]) * s_, (v1[2] * ss[3] + v1[3] * cc[3]) * s_);
;                         *(u32x4*)(rowp + bj * HALF) = w;
.LBB0_787:
	v_add_u32_e32 v18, 0xb0, v210
	v_mov_b64_e32 v[16:17], s[64:65]
	v_mad_i64_i32 v[16:17], s[16:17], v18, s47, v[16:17]
	s_waitcnt vmcnt(9)
	v_mov_b32_e32 v18, v64
	s_waitcnt vmcnt(8)
	v_mov_b32_e32 v19, v68
	s_waitcnt lgkmcnt(0)
	v_pk_mul_f32 v[20:21], v[12:13], v[18:19]
	v_mov_b32_e32 v24, v70
	v_sub_f32_e32 v20, v20, v21
	s_waitcnt vmcnt(7)
	v_mul_f32_e32 v22, v107, v20
	v_mov_b32_e32 v20, v68
	v_mov_b32_e32 v21, v64
	v_pk_mul_f32 v[12:13], v[12:13], v[20:21]
	v_mov_b32_e32 v68, v65
	v_add_f32_e32 v12, v13, v12
	v_mul_f32_e32 v12, v107, v12
	v_mov_b32_e32 v64, v69
	v_cvt_pk_bf16_f32 v12, v22, v12
	v_pk_mul_f32 v[22:23], v[14:15], v[68:69]
	v_pk_mul_f32 v[14:15], v[14:15], v[64:65]
	v_sub_f32_e32 v13, v22, v23
	v_add_f32_e32 v14, v15, v14
	v_mul_f32_e32 v13, v107, v13
	v_mul_f32_e32 v14, v107, v14
	v_mov_b32_e32 v22, v66
	v_mov_b32_e32 v23, v70
	v_mov_b32_e32 v25, v66
	v_cvt_pk_bf16_f32 v13, v13, v14
	v_pk_mul_f32 v[14:15], v[8:9], v[22:23]
	v_pk_mul_f32 v[8:9], v[8:9], v[24:25]
	v_sub_f32_e32 v14, v14, v15
	v_add_f32_e32 v8, v9, v8
	v_mul_f32_e32 v14, v107, v14
	v_mul_f32_e32 v8, v107, v8
	v_mov_b32_e32 v70, v67
	v_cvt_pk_bf16_f32 v14, v14, v8
	v_pk_mul_f32 v[8:9], v[10:11], v[70:71]
	v_mov_b32_e32 v66, v71
	v_sub_f32_e32 v8, v8, v9
	v_mul_f32_e32 v15, v107, v8
	v_pk_mul_f32 v[8:9], v[10:11], v[66:67]
	v_lshl_add_u64 v[16:17], v[162:163], 1, v[16:17]
	v_add_f32_e32 v8, v9, v8
	s_and_b64 vcc, exec, s[6:7]
	v_mul_f32_e32 v8, v107, v8
	v_cvt_pk_bf16_f32 v15, v15, v8
	global_store_dwordx4 v[16:17], v[12:15], off nt
	s_cbranch_vccnz .LBB0_805
	v_cmp_lt_i32_e32 vcc, v228, v222
	s_nop 1
	v_cndmask_b32_e32 v8, v221, v228, vcc
	v_lshlrev_b32_e32 v10, 2, v8
	ds_bpermute_b32 v8, v10, v12
	s_and_saveexec_b64 s[16:17], s[2:3]
	s_xor_b64 s[16:17], exec, s[16:17]
	s_cbranch_execz .LBB0_790
	s_waitcnt lgkmcnt(0)
	v_lshrrev_b32_e32 v8, 16, v8
	v_and_or_b32 v11, v12, s60, v8

; __device__ __forceinline__ unsigned cvt_pk_bf16(float lo, float hi) { unsigned r; asm volatile("v_cvt_pk_bf16_f32 %0, %1, %2" : "=v"(r) : "v"(lo), "v"(hi)); return r; }
;     __device__ __forceinline__ void operator()(const f32x4 (&acc)[2][2][4][2], const Unit& u, int wr, int wc, int fr, int fq) const {
;     ...
;                         const float s_ = sc[m][bj]; const f32x4 cc = c4[m], ss = s4[m];
;                         const f32x4 v0 = acc[ai][bj][m][0], v1 = acc[ai][bj][m][1];
;                         u32x4 w;
;                         w.x = cvt_pk_bf16((v0[0] * cc[0] - v0[1] * ss[0]) * s_, (v0[0] * ss[0] + v0[1] * cc[0]) * s_);
;                         w.y = cvt_pk_bf16((v0[2] * cc[1] - v0[3] * ss[1]) * s_, (v0[2] * ss[1] + v0[3] * cc[1]) * s_);
;                         w.z = cvt_pk_bf16((v1[0] * cc[2] - v1[1] * ss[2]) * s_, (v1[0] * ss[2] + v1[1] * cc[2]) * s_);
;                         w.w = cvt_pk_bf16((v1[2] * cc[3] - v1[3] * ss[3]) * s_, (v1[2] * ss[3] + v1[3] * cc[3]) * s_);
;                         *(u32x4*)(rowp + bj * HALF) = w;
.LBB0_805:
	v_pk_mul_f32 v[8:9], v[4:5], v[18:19]
	v_pk_mul_f32 v[4:5], v[4:5], v[20:21]
	v_sub_f32_e32 v8, v8, v9
	v_add_f32_e32 v4, v5, v4
	s_waitcnt vmcnt(7)
	v_mul_f32_e32 v8, v106, v8
	v_mul_f32_e32 v4, v106, v4
	v_cvt_pk_bf16_f32 v4, v8, v4
	v_pk_mul_f32 v[8:9], v[6:7], v[68:69]
	v_pk_mul_f32 v[6:7], v[6:7], v[64:65]
	v_sub_f32_e32 v5, v8, v9
	v_add_f32_e32 v6, v7, v6
	v_mul_f32_e32 v5, v106, v5
	v_mul_f32_e32 v6, v106, v6
	v_cvt_pk_bf16_f32 v5, v5, v6
	v_pk_mul_f32 v[6:7], v[0:1], v[22:23]
	v_pk_mul_f32 v[0:1], v[0:1], v[24:25]
	v_sub_f32_e32 v6, v6, v7
	v_add_f32_e32 v0, v1, v0
	v_mul_f32_e32 v6, v106, v6
	v_mul_f32_e32 v0, v106, v0
	v_cvt_pk_bf16_f32 v6, v6, v0
	v_pk_mul_f32 v[0:1], v[2:3], v[70:71]
	s_and_b64 vcc, exec, s[6:7]
	v_sub_f32_e32 v0, v0, v1
	v_mul_f32_e32 v7, v106, v0
	v_pk_mul_f32 v[0:1], v[2:3], v[66:67]
	s_nop 0
	v_add_f32_e32 v0, v1, v0
	v_mul_f32_e32 v0, v106, v0
	v_cvt_pk_bf16_f32 v7, v7, v0
	global_store_dwordx4 v[16:17], v[4:7], off offset:256 nt
	s_cbranch_vccnz .LBB0_823
	v_cmp_lt_i32_e32 vcc, v228, v222
	s_nop 1
	v_cndmask_b32_e32 v0, v221, v228, vcc
	v_lshlrev_b32_e32 v2, 2, v0
	ds_bpermute_b32 v0, v2, v4
	s_and_saveexec_b64 s[6:7], s[2:3]
	s_xor_b64 s[6:7], exec, s[6:7]
	s_cbranch_execz .LBB0_808
	s_waitcnt lgkmcnt(0)
	v_lshrrev_b32_e32 v0, 16, v0
	v_and_or_b32 v3, v4, s60, v0
